# grid-barrier spin back-off: s_sleep 1 -> s_sleep 2 in every poll loop (less polling traffic from waiting workgroups)
# speedup vs baseline: 1.0094x; 1.0094x over previous
; __global__ void __launch_bounds__(512, 2) mk_fwd(Args args) {
;     ...
;     if (hi > NPHASE) grid.sync();
.LBB0_18:
	s_sleep 2
	global_load_dword v2, v0, s[0:1] offset:32 sc1
	s_waitcnt vmcnt(0)
	v_and_b32_e32 v2, 0xffff0000, v2
	v_cmp_ne_u32_e32 vcc, v2, v1
	s_or_b64 s[6:7], vcc, s[6:7]
	s_andn2_b64 exec, exec, s[6:7]
	s_cbranch_execnz .LBB0_18

; __device__ __forceinline__ unsigned xb_ld(unsigned* p)              { return __hip_atomic_load(p, __ATOMIC_RELAXED, __HIP_MEMORY_SCOPE_AGENT); }
; __device__ __forceinline__ void xcd_barrier_complete(unsigned* bar, unsigned x, unsigned& nloc, unsigned& nx) {
;     const unsigned G = gridDim.x * gridDim.y * gridDim.z;
;     unsigned sum, cnt, mine, sp = 0u;
;     for (;;) {
;         sum = 0u; cnt = 0u; mine = 0u;
; #pragma unroll
;         for (unsigned j = 0; j < 16; ++j) { const unsigned c = xb_ld(&bar[XB_XCNT(j)]); sum += c; cnt += (c > 0u) ? 1u : 0u; mine = (j == x) ? c : mine; }
;         if (sum == G) break;
;         __builtin_amdgcn_s_sleep(1);
;         if ((++sp & 255u) == 0u) { if (xb_ld(&bar[XB_TMO])) break; if (sp > XB_SPIN_CAP) { atomicAdd(&bar[XB_TMO], 1u); break; } }
;     }
;     nloc = mine > 0u ? mine : 1u; nx = cnt > 0u ? cnt : 1u;
; }
.LBB0_72:
	global_load_dword v15, v16, s[8:9] sc1
	s_waitcnt lgkmcnt(0)
	global_load_dword v0, v16, s[10:11] sc1
	global_load_dword v1, v16, s[14:15] sc1
	global_load_dword v2, v16, s[16:17] sc1
	global_load_dword v3, v16, s[18:19] sc1
	global_load_dword v4, v16, s[20:21] sc1
	global_load_dword v5, v16, s[22:23] sc1
	global_load_dword v6, v16, s[24:25] sc1
	global_load_dword v7, v16, s[26:27] sc1
	global_load_dword v8, v16, s[28:29] sc1
	global_load_dword v9, v16, s[30:31] sc1
	global_load_dword v10, v16, s[34:35] sc1
	global_load_dword v11, v16, s[36:37] sc1
	global_load_dword v12, v16, s[38:39] sc1
	global_load_dword v13, v16, s[40:41] sc1
	global_load_dword v14, v16, s[42:43] sc1
	s_mov_b64 s[44:45], -1
	s_mov_b64 s[48:49], -1
	s_waitcnt vmcnt(14)
	v_add_u32_e32 v17, v0, v15
	s_waitcnt vmcnt(13)
	v_add_u32_e32 v17, v17, v1
	s_waitcnt vmcnt(12)
	v_add_u32_e32 v17, v17, v2
	s_waitcnt vmcnt(11)
	v_add_u32_e32 v17, v17, v3
	s_waitcnt vmcnt(10)
	v_add_u32_e32 v17, v17, v4
	s_waitcnt vmcnt(9)
	v_add_u32_e32 v17, v17, v5
	s_waitcnt vmcnt(8)
	v_add_u32_e32 v17, v17, v6
	s_waitcnt vmcnt(7)
	v_add_u32_e32 v17, v17, v7
	s_waitcnt vmcnt(6)
	v_add_u32_e32 v17, v17, v8
	s_waitcnt vmcnt(5)
	v_add_u32_e32 v17, v17, v9
	s_waitcnt vmcnt(4)
	v_add_u32_e32 v17, v17, v10
	s_waitcnt vmcnt(3)
	v_add_u32_e32 v17, v17, v11
	s_waitcnt vmcnt(2)
	v_add_u32_e32 v17, v17, v12
	s_waitcnt vmcnt(1)
	v_add_u32_e32 v17, v17, v13
	s_waitcnt vmcnt(0)
	v_add_u32_e32 v17, v17, v14
	v_cmp_eq_u32_e32 vcc, s52, v17
	s_cbranch_vccnz .LBB0_71
	s_and_b32 s44, s53, 0xff
	s_cmp_eq_u32 s44, 0
	s_mov_b64 s[44:45], -1
	s_mov_b64 s[50:51], -1
	s_sleep 2
	s_cbranch_scc0 .LBB0_76
	global_load_dword v17, v16, s[6:7] sc1
	s_waitcnt vmcnt(0)
	v_cmp_eq_u32_e32 vcc, 0, v17
	s_cbranch_vccnz .LBB0_78
	s_mov_b64 s[50:51], 0

.LBB0_90:
	s_and_b32 s24, s28, 0xff
	s_mov_b64 s[22:23], -1
	s_cmp_lg_u32 s24, 0
	s_mov_b64 s[26:27], -1
	s_sleep 2
	s_cbranch_scc1 .LBB0_93
	global_load_dword v2, v0, s[14:15] sc1
	s_waitcnt vmcnt(0)
	v_cmp_eq_u32_e32 vcc, 0, v2
	s_cbranch_vccnz .LBB0_95
	s_mov_b64 s[26:27], 0
	s_mov_b64 s[24:25], -1

.LBB0_107:
	s_and_b32 s22, s28, 0xff
	s_cmp_lg_u32 s22, 0
	s_mov_b64 s[24:25], -1
	s_sleep 2
	s_cbranch_scc1 .LBB0_110
	global_load_dword v1, v0, s[14:15] sc1
	s_waitcnt vmcnt(0)
	v_cmp_eq_u32_e32 vcc, 0, v1
	s_cbranch_vccnz .LBB0_112
	s_mov_b64 s[24:25], 0
	s_mov_b64 s[22:23], -1

; __device__ __forceinline__ unsigned xb_ld(unsigned* p)              { return __hip_atomic_load(p, __ATOMIC_RELAXED, __HIP_MEMORY_SCOPE_AGENT); }
; __device__ __forceinline__ void xcd_barrier_complete(unsigned* bar, unsigned x, unsigned& nloc, unsigned& nx) {
;     const unsigned G = gridDim.x * gridDim.y * gridDim.z;
;     unsigned sum, cnt, mine, sp = 0u;
;     for (;;) {
;         sum = 0u; cnt = 0u; mine = 0u;
; #pragma unroll
;         for (unsigned j = 0; j < 16; ++j) { const unsigned c = xb_ld(&bar[XB_XCNT(j)]); sum += c; cnt += (c > 0u) ? 1u : 0u; mine = (j == x) ? c : mine; }
;         if (sum == G) break;
;         __builtin_amdgcn_s_sleep(1);
;         if ((++sp & 255u) == 0u) { if (xb_ld(&bar[XB_TMO])) break; if (sp > XB_SPIN_CAP) { atomicAdd(&bar[XB_TMO], 1u); break; } }
;     }
.LBB0_180:
	v_readlane_b32 s6, v254, 8
	v_readlane_b32 s7, v254, 9
	global_load_dword v5, v193, s[88:89] sc1
	s_waitcnt lgkmcnt(0)
	global_load_dword v0, v193, s[90:91] sc1
	global_load_dword v1, v193, s[92:93] sc1
	global_load_dword v2, v193, s[76:77] sc1
	global_load_dword v3, v193, s[70:71] sc1
	global_load_dword v4, v193, s[72:73] sc1
	global_load_dword v6, v193, s[6:7] sc1
	v_readlane_b32 s6, v254, 10
	v_readlane_b32 s7, v254, 11
	s_mov_b64 s[38:39], -1
	s_mov_b64 s[40:41], -1
	s_waitcnt vmcnt(5)
	v_add_u32_e32 v16, v0, v5
	s_nop 0
	global_load_dword v7, v193, s[6:7] sc1
	v_readlane_b32 s6, v254, 12
	v_readlane_b32 s7, v254, 13
	s_waitcnt vmcnt(5)
	v_add_u32_e32 v16, v16, v1
	s_waitcnt vmcnt(4)
	v_add_u32_e32 v16, v16, v2
	s_waitcnt vmcnt(3)
	v_add_u32_e32 v16, v16, v3
	s_waitcnt vmcnt(2)
	v_add_u32_e32 v16, v16, v4
	s_waitcnt vmcnt(1)
	v_add_u32_e32 v16, v16, v6
	global_load_dword v8, v193, s[6:7] sc1
	v_readlane_b32 s6, v254, 14
	v_readlane_b32 s7, v254, 15
	s_waitcnt vmcnt(1)
	v_add_u32_e32 v16, v16, v7
	s_nop 2
	global_load_dword v9, v193, s[6:7] sc1
	v_readlane_b32 s6, v254, 16
	v_readlane_b32 s7, v254, 17
	s_waitcnt vmcnt(1)
	v_add_u32_e32 v16, v16, v8
	s_nop 2
	global_load_dword v10, v193, s[6:7] sc1
	v_readlane_b32 s6, v254, 18
	v_readlane_b32 s7, v254, 19
	s_waitcnt vmcnt(1)
	v_add_u32_e32 v16, v16, v9
	s_nop 2
	global_load_dword v11, v193, s[6:7] sc1
	v_readlane_b32 s6, v254, 20
	v_readlane_b32 s7, v254, 21
	s_waitcnt vmcnt(1)
	v_add_u32_e32 v16, v16, v10
	s_nop 2
	global_load_dword v12, v193, s[6:7] sc1
	v_readlane_b32 s6, v254, 22
	v_readlane_b32 s7, v254, 23
	s_waitcnt vmcnt(1)
	v_add_u32_e32 v16, v16, v11
	s_nop 2
	global_load_dword v13, v193, s[6:7] sc1
	v_readlane_b32 s6, v254, 24
	v_readlane_b32 s7, v254, 25
	s_waitcnt vmcnt(1)
	v_add_u32_e32 v16, v16, v12
	s_nop 2
	global_load_dword v14, v193, s[6:7] sc1
	v_readlane_b32 s6, v254, 26
	v_readlane_b32 s7, v254, 27
	s_waitcnt vmcnt(1)
	v_add_u32_e32 v16, v16, v13
	s_nop 2
	global_load_dword v15, v193, s[6:7] sc1
	s_waitcnt vmcnt(1)
	v_add_u32_e32 v16, v16, v14
	s_waitcnt vmcnt(0)
	v_add_u32_e32 v16, v16, v15
	v_cmp_eq_u32_e32 vcc, s26, v16
	s_cbranch_vccnz .LBB0_179
	s_and_b32 s6, s5, 0xff
	s_cmp_eq_u32 s6, 0
	s_mov_b64 s[42:43], -1
	s_sleep 2
	s_cbranch_scc0 .LBB0_184
	global_load_dword v16, v193, s[44:45] sc1
	s_waitcnt vmcnt(0)
	v_cmp_eq_u32_e32 vcc, 0, v16
	s_cbranch_vccnz .LBB0_186
	s_mov_b64 s[42:43], 0

.LBB0_199:
	s_and_b32 s6, s5, 0xff
	s_mov_b64 s[72:73], -1
	s_cmp_lg_u32 s6, 0
	s_mov_b64 s[76:77], -1
	s_sleep 2
	s_cbranch_scc1 .LBB0_202
	global_load_dword v0, v193, s[44:45] sc1
	s_waitcnt vmcnt(0)
	v_cmp_eq_u32_e32 vcc, 0, v0
	s_cbranch_vccnz .LBB0_204
	s_mov_b64 s[76:77], 0
	s_mov_b64 s[74:75], -1

; __device__ __forceinline__ unsigned xb_ld(unsigned* p)              { return __hip_atomic_load(p, __ATOMIC_RELAXED, __HIP_MEMORY_SCOPE_AGENT); }
; __device__ __forceinline__ void xcd_barrier_complete(unsigned* bar, unsigned x, unsigned& nloc, unsigned& nx) {
;     const unsigned G = gridDim.x * gridDim.y * gridDim.z;
;     unsigned sum, cnt, mine, sp = 0u;
;     for (;;) {
;         sum = 0u; cnt = 0u; mine = 0u;
; #pragma unroll
;         for (unsigned j = 0; j < 16; ++j) { const unsigned c = xb_ld(&bar[XB_XCNT(j)]); sum += c; cnt += (c > 0u) ? 1u : 0u; mine = (j == x) ? c : mine; }
;         if (sum == G) break;
;         __builtin_amdgcn_s_sleep(1);
;         if ((++sp & 255u) == 0u) { if (xb_ld(&bar[XB_TMO])) break; if (sp > XB_SPIN_CAP) { atomicAdd(&bar[XB_TMO], 1u); break; } }
;     }
.LBB0_308:
	v_readlane_b32 s2, v254, 8
	v_readlane_b32 s3, v254, 9
	global_load_dword v5, v193, s[88:89] sc1
	s_waitcnt lgkmcnt(0)
	global_load_dword v0, v193, s[90:91] sc1
	global_load_dword v1, v193, s[92:93] sc1
	global_load_dword v2, v193, s[76:77] sc1
	global_load_dword v3, v193, s[70:71] sc1
	global_load_dword v4, v193, s[72:73] sc1
	global_load_dword v6, v193, s[2:3] sc1
	v_readlane_b32 s2, v254, 10
	v_readlane_b32 s3, v254, 11
	s_mov_b64 s[38:39], -1
	s_waitcnt vmcnt(5)
	v_add_u32_e32 v16, v0, v5
	s_nop 1
	global_load_dword v7, v193, s[2:3] sc1
	v_readlane_b32 s2, v254, 12
	v_readlane_b32 s3, v254, 13
	s_waitcnt vmcnt(5)
	v_add_u32_e32 v16, v16, v1
	s_waitcnt vmcnt(4)
	v_add_u32_e32 v16, v16, v2
	s_waitcnt vmcnt(3)
	v_add_u32_e32 v16, v16, v3
	s_waitcnt vmcnt(2)
	v_add_u32_e32 v16, v16, v4
	s_waitcnt vmcnt(1)
	v_add_u32_e32 v16, v16, v6
	global_load_dword v8, v193, s[2:3] sc1
	v_readlane_b32 s2, v254, 14
	v_readlane_b32 s3, v254, 15
	s_waitcnt vmcnt(1)
	v_add_u32_e32 v16, v16, v7
	s_nop 2
	global_load_dword v9, v193, s[2:3] sc1
	v_readlane_b32 s2, v254, 16
	v_readlane_b32 s3, v254, 17
	s_waitcnt vmcnt(1)
	v_add_u32_e32 v16, v16, v8
	s_nop 2
	global_load_dword v10, v193, s[2:3] sc1
	v_readlane_b32 s2, v254, 18
	v_readlane_b32 s3, v254, 19
	s_waitcnt vmcnt(1)
	v_add_u32_e32 v16, v16, v9
	s_nop 2
	global_load_dword v11, v193, s[2:3] sc1
	v_readlane_b32 s2, v254, 20
	v_readlane_b32 s3, v254, 21
	s_waitcnt vmcnt(1)
	v_add_u32_e32 v16, v16, v10
	s_nop 2
	global_load_dword v12, v193, s[2:3] sc1
	v_readlane_b32 s2, v254, 22
	v_readlane_b32 s3, v254, 23
	s_waitcnt vmcnt(1)
	v_add_u32_e32 v16, v16, v11
	s_nop 2
	global_load_dword v13, v193, s[2:3] sc1
	v_readlane_b32 s2, v254, 24
	v_readlane_b32 s3, v254, 25
	s_waitcnt vmcnt(1)
	v_add_u32_e32 v16, v16, v12
	s_nop 2
	global_load_dword v14, v193, s[2:3] sc1
	v_readlane_b32 s2, v254, 26
	v_readlane_b32 s3, v254, 27
	s_waitcnt vmcnt(1)
	v_add_u32_e32 v16, v16, v13
	s_nop 2
	global_load_dword v15, v193, s[2:3] sc1
	s_mov_b64 s[2:3], -1
	s_waitcnt vmcnt(1)
	v_add_u32_e32 v16, v16, v14
	s_waitcnt vmcnt(0)
	v_add_u32_e32 v16, v16, v15
	v_cmp_eq_u32_e32 vcc, s26, v16
	s_cbranch_vccnz .LBB0_307
	s_and_b32 s2, s5, 0xff
	s_cmp_eq_u32 s2, 0
	s_mov_b64 s[2:3], -1
	s_mov_b64 s[40:41], -1
	s_sleep 2
	s_cbranch_scc0 .LBB0_312
	global_load_dword v16, v193, s[44:45] sc1
	s_waitcnt vmcnt(0)
	v_cmp_eq_u32_e32 vcc, 0, v16
	s_cbranch_vccnz .LBB0_314
	s_mov_b64 s[40:41], 0

.LBB0_326:
	s_and_b32 s6, s5, 0xff
	s_mov_b64 s[70:71], -1
	s_cmp_lg_u32 s6, 0
	s_mov_b64 s[74:75], -1
	s_sleep 2
	s_cbranch_scc1 .LBB0_329
	global_load_dword v0, v193, s[44:45] sc1
	s_waitcnt vmcnt(0)
	v_cmp_eq_u32_e32 vcc, 0, v0
	s_cbranch_vccnz .LBB0_331
	s_mov_b64 s[74:75], 0
	s_mov_b64 s[72:73], -1

; __device__ __forceinline__ unsigned xb_ld(unsigned* p)              { return __hip_atomic_load(p, __ATOMIC_RELAXED, __HIP_MEMORY_SCOPE_AGENT); }
; __device__ __forceinline__ void xcd_barrier_complete(unsigned* bar, unsigned x, unsigned& nloc, unsigned& nx) {
;     const unsigned G = gridDim.x * gridDim.y * gridDim.z;
;     unsigned sum, cnt, mine, sp = 0u;
;     for (;;) {
;         sum = 0u; cnt = 0u; mine = 0u;
; #pragma unroll
;         for (unsigned j = 0; j < 16; ++j) { const unsigned c = xb_ld(&bar[XB_XCNT(j)]); sum += c; cnt += (c > 0u) ? 1u : 0u; mine = (j == x) ? c : mine; }
;         if (sum == G) break;
;         __builtin_amdgcn_s_sleep(1);
;         if ((++sp & 255u) == 0u) { if (xb_ld(&bar[XB_TMO])) break; if (sp > XB_SPIN_CAP) { atomicAdd(&bar[XB_TMO], 1u); break; } }
;     }
.LBB0_749:
	v_readlane_b32 s2, v254, 8
	v_readlane_b32 s3, v254, 9
	global_load_dword v5, v193, s[88:89] sc1
	s_waitcnt lgkmcnt(0)
	global_load_dword v0, v193, s[90:91] sc1
	global_load_dword v1, v193, s[92:93] sc1
	global_load_dword v2, v193, s[76:77] sc1
	global_load_dword v3, v193, s[70:71] sc1
	global_load_dword v4, v193, s[72:73] sc1
	global_load_dword v6, v193, s[2:3] sc1
	v_readlane_b32 s2, v254, 10
	v_readlane_b32 s3, v254, 11
	s_mov_b64 s[38:39], -1
	s_waitcnt vmcnt(5)
	v_add_u32_e32 v16, v0, v5
	s_nop 1
	global_load_dword v7, v193, s[2:3] sc1
	v_readlane_b32 s2, v254, 12
	v_readlane_b32 s3, v254, 13
	s_waitcnt vmcnt(5)
	v_add_u32_e32 v16, v16, v1
	s_waitcnt vmcnt(4)
	v_add_u32_e32 v16, v16, v2
	s_waitcnt vmcnt(3)
	v_add_u32_e32 v16, v16, v3
	s_waitcnt vmcnt(2)
	v_add_u32_e32 v16, v16, v4
	s_waitcnt vmcnt(1)
	v_add_u32_e32 v16, v16, v6
	global_load_dword v8, v193, s[2:3] sc1
	v_readlane_b32 s2, v254, 14
	v_readlane_b32 s3, v254, 15
	s_waitcnt vmcnt(1)
	v_add_u32_e32 v16, v16, v7
	s_nop 2
	global_load_dword v9, v193, s[2:3] sc1
	v_readlane_b32 s2, v254, 16
	v_readlane_b32 s3, v254, 17
	s_waitcnt vmcnt(1)
	v_add_u32_e32 v16, v16, v8
	s_nop 2
	global_load_dword v10, v193, s[2:3] sc1
	v_readlane_b32 s2, v254, 18
	v_readlane_b32 s3, v254, 19
	s_waitcnt vmcnt(1)
	v_add_u32_e32 v16, v16, v9
	s_nop 2
	global_load_dword v11, v193, s[2:3] sc1
	v_readlane_b32 s2, v254, 20
	v_readlane_b32 s3, v254, 21
	s_waitcnt vmcnt(1)
	v_add_u32_e32 v16, v16, v10
	s_nop 2
	global_load_dword v12, v193, s[2:3] sc1
	v_readlane_b32 s2, v254, 22
	v_readlane_b32 s3, v254, 23
	s_waitcnt vmcnt(1)
	v_add_u32_e32 v16, v16, v11
	s_nop 2
	global_load_dword v13, v193, s[2:3] sc1
	v_readlane_b32 s2, v254, 24
	v_readlane_b32 s3, v254, 25
	s_waitcnt vmcnt(1)
	v_add_u32_e32 v16, v16, v12
	s_nop 2
	global_load_dword v14, v193, s[2:3] sc1
	v_readlane_b32 s2, v254, 26
	v_readlane_b32 s3, v254, 27
	s_waitcnt vmcnt(1)
	v_add_u32_e32 v16, v16, v13
	s_nop 2
	global_load_dword v15, v193, s[2:3] sc1
	s_mov_b64 s[2:3], -1
	s_waitcnt vmcnt(1)
	v_add_u32_e32 v16, v16, v14
	s_waitcnt vmcnt(0)
	v_add_u32_e32 v16, v16, v15
	v_cmp_eq_u32_e32 vcc, s26, v16
	s_cbranch_vccnz .LBB0_748
	s_and_b32 s2, s4, 0xff
	s_cmp_eq_u32 s2, 0
	s_mov_b64 s[2:3], -1
	s_mov_b64 s[40:41], -1
	s_sleep 2
	s_cbranch_scc0 .LBB0_753
	global_load_dword v16, v193, s[44:45] sc1
	s_waitcnt vmcnt(0)
	v_cmp_eq_u32_e32 vcc, 0, v16
	s_cbranch_vccnz .LBB0_755
	s_mov_b64 s[40:41], 0

.LBB0_767:
	s_and_b32 s5, s4, 0xff
	s_mov_b64 s[68:69], -1
	s_cmp_lg_u32 s5, 0
	s_mov_b64 s[72:73], -1
	s_sleep 2
	s_cbranch_scc1 .LBB0_770
	global_load_dword v0, v193, s[44:45] sc1
	s_waitcnt vmcnt(0)
	v_cmp_eq_u32_e32 vcc, 0, v0
	s_cbranch_vccnz .LBB0_772
	s_mov_b64 s[72:73], 0
	s_mov_b64 s[70:71], -1
